# in-proj GEMM K-loop: second-operand (B0) fragment LDS reads of each K-tile issued between the MFMAs of the preceding block instead of in the load segment
# speedup vs baseline: 1.0274x; 1.0033x over previous
; #define PG8_STAGE(bufoff, gbase, voff) do { _Pragma("unroll") for (int _i = 0; _i < 2; ++_i) \
;         __builtin_amdgcn_global_load_lds((const unsigned*)((const char*)(gbase) + (voff)[_i]), (LAS unsigned*)(lds + (bufoff) + ldsw + _i * 8192), 16, 0, 0); } while (0)
; #define PG8_LDA(dst, b, h) do { _Pragma("unroll") for (int m = 0; m < 4; ++m) _Pragma("unroll") for (int k = 0; k < 2; ++k) dst[m][k] = *(const LAS bf16x8*)(lds + PG8_SA(b, h) + aoff + m * 2048 + k * 1024); } while (0)
; #define PG8_LDB(dst, b, h) do { _Pragma("unroll") for (int n = 0; n < 2; ++n) _Pragma("unroll") for (int k = 0; k < 2; ++k) dst[n][k] = *(const LAS bf16x8*)(lds + PG8_SB(b, h) + boff + n * 2048 + k * 1024); } while (0)
; #define PG8_MMA(ai, bj, At, Bt) do { __builtin_amdgcn_s_setprio(1); _Pragma("unroll") for (int m = 0; m < 4; ++m) _Pragma("unroll") for (int n = 0; n < 2; ++n) _Pragma("unroll") for (int k = 0; k < 2; ++k) \
;         acc[ai][bj][m][n] = __builtin_amdgcn_mfma_f32_16x16x32_bf16(Bt[n][k], At[m][k], acc[ai][bj][m][n], 0, 0, 0); __builtin_amdgcn_s_setprio(0); } while (0)
; #define PG8_WAIT_L(n) asm volatile("s_waitcnt lgkmcnt(" #n ")" ::: "memory")
; #define PG8_BAR __builtin_amdgcn_s_barrier()
; #define PG8_SCHED __builtin_amdgcn_sched_barrier(0)
; template <class Epi, class Sched>
; __device__ __forceinline__ void gemm_phase(const int TID, LAS unsigned char* lds, const int lda, const int ldb, const Sched& S, const Epi& E) {
;     ...
;             PG8_LDB(B0, 0, 0); PG8_SCHED; PG8_LDA(At, 0, 0); PG8_STAGE(PG8_SA(1, 1), a1 + hA, voffA);
;             PG8_WAIT_L(8); PG8_BAR; PG8_WAIT_L(0); PG8_MMA(0, 0, At, B0); PG8_BAR; PG8_SCHED;
;             PG8_LDB(B1, 0, 1); PG8_STAGE(PG8_SB(0, 0), b2, voffB);
;             PG8_BAR; PG8_WAIT_L(0); PG8_MMA(0, 1, At, B1); PG8_BAR;
;             PG8_LDA(At, 0, 1); PG8_STAGE(PG8_SA(0, 0), a2, voffA);
;             PG8_BAR; PG8_WAIT_L(0); PG8_MMA(1, 0, At, B0); PG8_BAR; PG8_SCHED;
.LBB0_1228:
	v_add_u32_e32 v154, 0x10000, v13
	ds_read_b128 v[150:153], v154
	ds_read_b128 v[158:161], v154 offset:1024
	ds_read_b128 v[162:165], v154 offset:2048
	ds_read_b128 v[166:169], v154 offset:3072
.Lk1_body:
	s_add_u32 s8, s46, 0xfff80080
	s_addc_u32 s9, s47, -1
	s_add_i32 s10, 0, 0x10000
	s_cmp_eq_u32 s29, 28
	s_cselect_b32 s51, s43, s9
	s_cselect_b32 s50, s42, s8
	s_cselect_b32 s49, s45, s24
	s_cselect_b32 s48, s44, s3
	v_lshl_add_u64 v[154:155], s[46:47], 0, v[148:149]
	s_add_i32 m0, s57, 0xc000
	ds_read_b128 v[170:173], v157
	ds_read_b128 v[174:177], v157 offset:1024
	ds_read_b128 v[178:181], v157 offset:2048
	ds_read_b128 v[196:199], v157 offset:3072
	ds_read_b128 v[200:203], v157 offset:4096
	ds_read_b128 v[204:207], v157 offset:5120
	ds_read_b128 v[208:211], v157 offset:6144
	ds_read_b128 v[212:215], v157 offset:7168
	global_load_lds_dwordx4 v[154:155], off
	v_lshl_add_u64 v[154:155], s[46:47], 0, v[146:147]
	s_add_i32 m0, s57, 0xe000
	s_nop 0
	global_load_lds_dwordx4 v[154:155], off
	s_waitcnt lgkmcnt(8)
	s_barrier
	s_waitcnt lgkmcnt(0)
	s_setprio 1
	s_waitcnt lgkmcnt(0)
	v_mfma_f32_16x16x32_bf16 v[130:133], v[150:153], v[170:173], v[130:133]
	v_mfma_f32_16x16x32_bf16 v[126:129], v[162:165], v[170:173], v[126:129]
	v_mfma_f32_16x16x32_bf16 v[114:117], v[150:153], v[178:181], v[114:117]
	v_mfma_f32_16x16x32_bf16 v[110:113], v[162:165], v[178:181], v[110:113]
	v_mfma_f32_16x16x32_bf16 v[98:101], v[150:153], v[200:203], v[98:101]
	v_mfma_f32_16x16x32_bf16 v[94:97], v[162:165], v[200:203], v[94:97]
	v_mfma_f32_16x16x32_bf16 v[82:85], v[150:153], v[208:211], v[82:85]
	v_mfma_f32_16x16x32_bf16 v[78:81], v[162:165], v[208:211], v[78:81]
	v_mfma_f32_16x16x32_bf16 v[130:133], v[158:161], v[174:177], v[130:133]
	v_mfma_f32_16x16x32_bf16 v[126:129], v[166:169], v[174:177], v[126:129]
	v_mfma_f32_16x16x32_bf16 v[114:117], v[158:161], v[196:199], v[114:117]
	v_mfma_f32_16x16x32_bf16 v[110:113], v[166:169], v[196:199], v[110:113]
	v_mfma_f32_16x16x32_bf16 v[98:101], v[158:161], v[204:207], v[98:101]
	v_mfma_f32_16x16x32_bf16 v[94:97], v[166:169], v[204:207], v[94:97]
	v_mfma_f32_16x16x32_bf16 v[82:85], v[158:161], v[212:215], v[82:85]
	v_mfma_f32_16x16x32_bf16 v[78:81], v[166:169], v[212:215], v[78:81]
	s_setprio 0
	s_barrier
	s_add_i32 s8, 0, 0x14000
	v_add_u32_e32 v154, s8, v13
	s_add_i32 s9, s10, s56
	ds_read_b128 v[216:219], v154
	ds_read_b128 v[220:223], v154 offset:1024
	ds_read_b128 v[236:239], v154 offset:2048
	ds_read_b128 v[240:243], v154 offset:3072
	v_lshl_add_u64 v[154:155], s[48:49], 0, v[136:137]
	s_mov_b32 m0, s9
	v_lshl_add_u64 v[186:187], s[48:49], 0, v[140:141]
	global_load_lds_dwordx4 v[154:155], off
	s_add_i32 m0, s9, 0x2000
	s_nop 0
	global_load_lds_dwordx4 v[186:187], off
	s_barrier
	s_waitcnt lgkmcnt(0)
	s_setprio 1
	s_waitcnt lgkmcnt(0)
	v_mfma_f32_16x16x32_bf16 v[122:125], v[216:219], v[170:173], v[122:125]
	v_mfma_f32_16x16x32_bf16 v[118:121], v[236:239], v[170:173], v[118:121]
	v_mfma_f32_16x16x32_bf16 v[106:109], v[216:219], v[178:181], v[106:109]
	v_mfma_f32_16x16x32_bf16 v[102:105], v[236:239], v[178:181], v[102:105]
	v_mfma_f32_16x16x32_bf16 v[90:93], v[216:219], v[200:203], v[90:93]
	v_mfma_f32_16x16x32_bf16 v[86:89], v[236:239], v[200:203], v[86:89]
	v_mfma_f32_16x16x32_bf16 v[74:77], v[216:219], v[208:211], v[74:77]
	v_mfma_f32_16x16x32_bf16 v[70:73], v[236:239], v[208:211], v[70:73]
	v_mfma_f32_16x16x32_bf16 v[122:125], v[220:223], v[174:177], v[122:125]
	v_mfma_f32_16x16x32_bf16 v[118:121], v[240:243], v[174:177], v[118:121]
	v_mfma_f32_16x16x32_bf16 v[106:109], v[220:223], v[196:199], v[106:109]
	v_mfma_f32_16x16x32_bf16 v[102:105], v[240:243], v[196:199], v[102:105]
	v_mfma_f32_16x16x32_bf16 v[90:93], v[220:223], v[204:207], v[90:93]
	v_mfma_f32_16x16x32_bf16 v[86:89], v[240:243], v[204:207], v[86:89]
	v_mfma_f32_16x16x32_bf16 v[74:77], v[220:223], v[212:215], v[74:77]
	v_mfma_f32_16x16x32_bf16 v[70:73], v[240:243], v[212:215], v[70:73]
	s_setprio 0
	s_mov_b32 m0, s57
	v_lshl_add_u64 v[188:189], s[50:51], 0, v[134:135]
	s_barrier
	ds_read_b128 v[170:173], v157 offset:16384
	ds_read_b128 v[174:177], v157 offset:17408
	ds_read_b128 v[178:181], v157 offset:18432
	ds_read_b128 v[196:199], v157 offset:19456
	ds_read_b128 v[200:203], v157 offset:20480
	ds_read_b128 v[204:207], v157 offset:21504
	ds_read_b128 v[208:211], v157 offset:22528
	ds_read_b128 v[212:215], v157 offset:23552
	global_load_lds_dwordx4 v[188:189], off
	v_lshl_add_u64 v[244:245], s[50:51], 0, v[138:139]
	s_mov_b32 m0, s58
	s_nop 0
	global_load_lds_dwordx4 v[244:245], off
	s_barrier
	s_waitcnt lgkmcnt(0)
	s_setprio 1
	s_waitcnt lgkmcnt(0)
	v_mfma_f32_16x16x32_bf16 v[66:69], v[150:153], v[170:173], v[66:69]
	v_mfma_f32_16x16x32_bf16 v[62:65], v[162:165], v[170:173], v[62:65]
	v_mfma_f32_16x16x32_bf16 v[50:53], v[150:153], v[178:181], v[50:53]
	v_mfma_f32_16x16x32_bf16 v[46:49], v[162:165], v[178:181], v[46:49]
	v_mfma_f32_16x16x32_bf16 v[34:37], v[150:153], v[200:203], v[34:37]
	v_mfma_f32_16x16x32_bf16 v[30:33], v[162:165], v[200:203], v[30:33]
	v_mfma_f32_16x16x32_bf16 v[18:21], v[150:153], v[208:211], v[18:21]
	v_mfma_f32_16x16x32_bf16 v[8:11], v[162:165], v[208:211], v[8:11]
	v_mfma_f32_16x16x32_bf16 v[66:69], v[158:161], v[174:177], v[66:69]
	v_mfma_f32_16x16x32_bf16 v[62:65], v[166:169], v[174:177], v[62:65]
	v_mfma_f32_16x16x32_bf16 v[50:53], v[158:161], v[196:199], v[50:53]
	v_mfma_f32_16x16x32_bf16 v[46:49], v[166:169], v[196:199], v[46:49]
	v_mfma_f32_16x16x32_bf16 v[34:37], v[158:161], v[204:207], v[34:37]
	v_mfma_f32_16x16x32_bf16 v[30:33], v[166:169], v[204:207], v[30:33]
	v_mfma_f32_16x16x32_bf16 v[18:21], v[158:161], v[212:215], v[18:21]
	v_mfma_f32_16x16x32_bf16 v[8:11], v[166:169], v[212:215], v[8:11]
	s_setprio 0
	s_barrier
; #define PG8_STAGE(bufoff, gbase, voff) do { _Pragma("unroll") for (int _i = 0; _i < 2; ++_i) \
;         __builtin_amdgcn_global_load_lds((const unsigned*)((const char*)(gbase) + (voff)[_i]), (LAS unsigned*)(lds + (bufoff) + ldsw + _i * 8192), 16, 0, 0); } while (0)
; #define PG8_LDA(dst, b, h) do { _Pragma("unroll") for (int m = 0; m < 4; ++m) _Pragma("unroll") for (int k = 0; k < 2; ++k) dst[m][k] = *(const LAS bf16x8*)(lds + PG8_SA(b, h) + aoff + m * 2048 + k * 1024); } while (0)
; #define PG8_LDB(dst, b, h) do { _Pragma("unroll") for (int n = 0; n < 2; ++n) _Pragma("unroll") for (int k = 0; k < 2; ++k) dst[n][k] = *(const LAS bf16x8*)(lds + PG8_SB(b, h) + boff + n * 2048 + k * 1024); } while (0)
; #define PG8_MMA(ai, bj, At, Bt) do { __builtin_amdgcn_s_setprio(1); _Pragma("unroll") for (int m = 0; m < 4; ++m) _Pragma("unroll") for (int n = 0; n < 2; ++n) _Pragma("unroll") for (int k = 0; k < 2; ++k) \
;         acc[ai][bj][m][n] = __builtin_amdgcn_mfma_f32_16x16x32_bf16(Bt[n][k], At[m][k], acc[ai][bj][m][n], 0, 0, 0); __builtin_amdgcn_s_setprio(0); } while (0)
; #define PG8_WAIT_V(n) asm volatile("s_waitcnt vmcnt(" #n ")" ::: "memory")
; #define PG8_WAIT_L(n) asm volatile("s_waitcnt lgkmcnt(" #n ")" ::: "memory")
; #define PG8_BAR __builtin_amdgcn_s_barrier()
; #define PG8_SCHED __builtin_amdgcn_sched_barrier(0)
; template <class Epi, class Sched>
; __device__ __forceinline__ void gemm_phase(const int TID, LAS unsigned char* lds, const int lda, const int ldb, const Sched& S, const Epi& E) {
;     ...
;             PG8_STAGE(PG8_SB(0, 1), b2 + hB, voffB);
;             PG8_WAIT_V(6); PG8_BAR; PG8_MMA(1, 1, At, B1); PG8_BAR;
;             PG8_LDB(B0, 1, 0); PG8_SCHED; PG8_LDA(At, 1, 0); PG8_STAGE(PG8_SA(0, 1), a2 + hA, voffA);
;             PG8_WAIT_L(8); PG8_BAR; PG8_WAIT_L(0); PG8_MMA(0, 0, At, B0); PG8_BAR; PG8_SCHED;
;             PG8_LDB(B1, 1, 1); PG8_STAGE(PG8_SB(1, 0), b3, voffB);
;             PG8_BAR; PG8_WAIT_L(0); PG8_MMA(0, 1, At, B1); PG8_BAR;
;             PG8_LDA(At, 1, 1); PG8_STAGE(PG8_SA(1, 0), a3, voffA);
	s_add_u32 s66, s48, 0x80000
	s_addc_u32 s67, s49, 0
	s_add_i32 s8, s8, s56
	v_lshl_add_u64 v[150:151], s[66:67], 0, v[136:137]
	s_mov_b32 m0, s8
	s_nop 0
	global_load_lds_dwordx4 v[150:151], off
	v_lshl_add_u64 v[150:151], s[66:67], 0, v[140:141]
	s_add_i32 m0, s8, 0x2000
	s_nop 0
	global_load_lds_dwordx4 v[150:151], off
	s_waitcnt vmcnt(6)
	s_barrier
	s_setprio 1
	v_add_u32_e32 v166, 0x18000, v13
	v_mfma_f32_16x16x32_bf16 v[58:61], v[216:219], v[170:173], v[58:61]
	v_mfma_f32_16x16x32_bf16 v[54:57], v[236:239], v[170:173], v[54:57]
	v_mfma_f32_16x16x32_bf16 v[42:45], v[216:219], v[178:181], v[42:45]
	v_mfma_f32_16x16x32_bf16 v[38:41], v[236:239], v[178:181], v[38:41]
	ds_read_b128 v[150:153], v166
	v_mfma_f32_16x16x32_bf16 v[26:29], v[216:219], v[200:203], v[26:29]
	v_mfma_f32_16x16x32_bf16 v[22:25], v[236:239], v[200:203], v[22:25]
	ds_read_b128 v[158:161], v166 offset:1024
	v_mfma_f32_16x16x32_bf16 v[4:7], v[216:219], v[208:211], v[4:7]
	v_mfma_f32_16x16x32_bf16 v[0:3], v[236:239], v[208:211], v[0:3]
	ds_read_b128 v[162:165], v166 offset:2048
	v_mfma_f32_16x16x32_bf16 v[58:61], v[220:223], v[174:177], v[58:61]
	v_mfma_f32_16x16x32_bf16 v[54:57], v[240:243], v[174:177], v[54:57]
	ds_read_b128 v[166:169], v166 offset:3072
	v_mfma_f32_16x16x32_bf16 v[42:45], v[220:223], v[196:199], v[42:45]
	v_mfma_f32_16x16x32_bf16 v[38:41], v[240:243], v[196:199], v[38:41]
	v_mfma_f32_16x16x32_bf16 v[26:29], v[220:223], v[204:207], v[26:29]
	v_mfma_f32_16x16x32_bf16 v[22:25], v[240:243], v[204:207], v[22:25]
	v_mfma_f32_16x16x32_bf16 v[4:7], v[220:223], v[212:215], v[4:7]
	v_mfma_f32_16x16x32_bf16 v[0:3], v[240:243], v[212:215], v[0:3]
	s_setprio 0
	s_add_i32 s8, 0, 0x18000
	s_barrier
	s_add_u32 s50, s50, 0x80000
	s_addc_u32 s51, s51, 0
	s_mov_b32 m0, s59
	v_lshl_add_u64 v[216:217], s[50:51], 0, v[134:135]
	ds_read_b128 v[170:173], v157 offset:32768
	ds_read_b128 v[174:177], v157 offset:33792
	ds_read_b128 v[178:181], v157 offset:34816
	ds_read_b128 v[196:199], v157 offset:35840
	ds_read_b128 v[200:203], v157 offset:36864
	ds_read_b128 v[204:207], v157 offset:37888
	ds_read_b128 v[208:211], v157 offset:38912
	ds_read_b128 v[212:215], v157 offset:39936
	global_load_lds_dwordx4 v[216:217], off
	v_lshl_add_u64 v[216:217], s[50:51], 0, v[138:139]
	s_mov_b32 m0, s60
	s_nop 0
	global_load_lds_dwordx4 v[216:217], off
	s_waitcnt lgkmcnt(8)
	s_barrier
	s_waitcnt lgkmcnt(0)
	s_setprio 1
	s_waitcnt lgkmcnt(0)
	v_mfma_f32_16x16x32_bf16 v[130:133], v[150:153], v[170:173], v[130:133]
	v_mfma_f32_16x16x32_bf16 v[126:129], v[162:165], v[170:173], v[126:129]
	v_mfma_f32_16x16x32_bf16 v[114:117], v[150:153], v[178:181], v[114:117]
	v_mfma_f32_16x16x32_bf16 v[110:113], v[162:165], v[178:181], v[110:113]
	v_mfma_f32_16x16x32_bf16 v[98:101], v[150:153], v[200:203], v[98:101]
	v_mfma_f32_16x16x32_bf16 v[94:97], v[162:165], v[200:203], v[94:97]
	v_mfma_f32_16x16x32_bf16 v[82:85], v[150:153], v[208:211], v[82:85]
	v_mfma_f32_16x16x32_bf16 v[78:81], v[162:165], v[208:211], v[78:81]
	v_mfma_f32_16x16x32_bf16 v[130:133], v[158:161], v[174:177], v[130:133]
	v_mfma_f32_16x16x32_bf16 v[126:129], v[166:169], v[174:177], v[126:129]
	v_mfma_f32_16x16x32_bf16 v[114:117], v[158:161], v[196:199], v[114:117]
	v_mfma_f32_16x16x32_bf16 v[110:113], v[166:169], v[196:199], v[110:113]
	v_mfma_f32_16x16x32_bf16 v[98:101], v[158:161], v[204:207], v[98:101]
	v_mfma_f32_16x16x32_bf16 v[94:97], v[166:169], v[204:207], v[94:97]
	v_mfma_f32_16x16x32_bf16 v[82:85], v[158:161], v[212:215], v[82:85]
	v_mfma_f32_16x16x32_bf16 v[78:81], v[166:169], v[212:215], v[78:81]
	s_setprio 0
	s_barrier
	s_add_i32 s9, 0, 0x1c000
	s_add_i32 s8, s8, s56
	v_add_u32_e32 v182, s9, v13
	v_lshl_add_u64 v[154:155], v[154:155], 0, s[36:37]
	s_mov_b32 m0, s8
	ds_read_b128 v[216:219], v182
	ds_read_b128 v[220:223], v182 offset:1024
	ds_read_b128 v[236:239], v182 offset:2048
	ds_read_b128 v[240:243], v182 offset:3072
	global_load_lds_dwordx4 v[154:155], off
	v_lshl_add_u64 v[154:155], v[186:187], 0, s[36:37]
	s_add_i32 m0, s8, 0x2000
	s_nop 0
	global_load_lds_dwordx4 v[154:155], off
	s_barrier
	s_waitcnt lgkmcnt(0)
	s_setprio 1
	s_waitcnt lgkmcnt(0)
	v_mfma_f32_16x16x32_bf16 v[122:125], v[216:219], v[170:173], v[122:125]
	v_mfma_f32_16x16x32_bf16 v[118:121], v[236:239], v[170:173], v[118:121]
	v_mfma_f32_16x16x32_bf16 v[106:109], v[216:219], v[178:181], v[106:109]
	v_mfma_f32_16x16x32_bf16 v[102:105], v[236:239], v[178:181], v[102:105]
	v_mfma_f32_16x16x32_bf16 v[90:93], v[216:219], v[200:203], v[90:93]
	v_mfma_f32_16x16x32_bf16 v[86:89], v[236:239], v[200:203], v[86:89]
	v_mfma_f32_16x16x32_bf16 v[74:77], v[216:219], v[208:211], v[74:77]
	v_mfma_f32_16x16x32_bf16 v[70:73], v[236:239], v[208:211], v[70:73]
	v_mfma_f32_16x16x32_bf16 v[122:125], v[220:223], v[174:177], v[122:125]
	v_mfma_f32_16x16x32_bf16 v[118:121], v[240:243], v[174:177], v[118:121]
	v_mfma_f32_16x16x32_bf16 v[106:109], v[220:223], v[196:199], v[106:109]
	v_mfma_f32_16x16x32_bf16 v[102:105], v[240:243], v[196:199], v[102:105]
	v_mfma_f32_16x16x32_bf16 v[90:93], v[220:223], v[204:207], v[90:93]
	v_mfma_f32_16x16x32_bf16 v[86:89], v[240:243], v[204:207], v[86:89]
	v_mfma_f32_16x16x32_bf16 v[74:77], v[220:223], v[212:215], v[74:77]
	v_mfma_f32_16x16x32_bf16 v[70:73], v[240:243], v[212:215], v[70:73]
	s_setprio 0
	s_mov_b32 m0, s62
	v_lshl_add_u64 v[154:155], v[188:189], 0, s[36:37]
	s_barrier
; #define PG8_STAGE(bufoff, gbase, voff) do { _Pragma("unroll") for (int _i = 0; _i < 2; ++_i) \
;         __builtin_amdgcn_global_load_lds((const unsigned*)((const char*)(gbase) + (voff)[_i]), (LAS unsigned*)(lds + (bufoff) + ldsw + _i * 8192), 16, 0, 0); } while (0)
; #define PG8_LDA(dst, b, h) do { _Pragma("unroll") for (int m = 0; m < 4; ++m) _Pragma("unroll") for (int k = 0; k < 2; ++k) dst[m][k] = *(const LAS bf16x8*)(lds + PG8_SA(b, h) + aoff + m * 2048 + k * 1024); } while (0)
; #define PG8_MMA(ai, bj, At, Bt) do { __builtin_amdgcn_s_setprio(1); _Pragma("unroll") for (int m = 0; m < 4; ++m) _Pragma("unroll") for (int n = 0; n < 2; ++n) _Pragma("unroll") for (int k = 0; k < 2; ++k) \
;         acc[ai][bj][m][n] = __builtin_amdgcn_mfma_f32_16x16x32_bf16(Bt[n][k], At[m][k], acc[ai][bj][m][n], 0, 0, 0); __builtin_amdgcn_s_setprio(0); } while (0)
; #define PG8_WAIT_V(n) asm volatile("s_waitcnt vmcnt(" #n ")" ::: "memory")
; #define PG8_WAIT_L(n) asm volatile("s_waitcnt lgkmcnt(" #n ")" ::: "memory")
; #define PG8_BAR __builtin_amdgcn_s_barrier()
; #define PG8_SCHED __builtin_amdgcn_sched_barrier(0)
; template <class Epi, class Sched>
; __device__ __forceinline__ void gemm_phase(const int TID, LAS unsigned char* lds, const int lda, const int ldb, const Sched& S, const Epi& E) {
;     ...
;             PG8_LDA(At, 1, 1); PG8_STAGE(PG8_SA(1, 0), a3, voffA);
;             PG8_BAR; PG8_WAIT_L(0); PG8_MMA(1, 0, At, B0); PG8_BAR; PG8_SCHED;
;             PG8_STAGE(PG8_SB(1, 1), b3 + hB, voffB);
;             PG8_WAIT_V(6); PG8_BAR; PG8_MMA(1, 1, At, B1); PG8_BAR;
	ds_read_b128 v[170:173], v157 offset:49152
	ds_read_b128 v[174:177], v157 offset:50176
	ds_read_b128 v[178:181], v157 offset:51200
	ds_read_b128 v[196:199], v157 offset:52224
	ds_read_b128 v[200:203], v157 offset:53248
	ds_read_b128 v[204:207], v157 offset:54272
	ds_read_b128 v[208:211], v157 offset:55296
	ds_read_b128 v[212:215], v157 offset:56320
	global_load_lds_dwordx4 v[154:155], off
	v_lshl_add_u64 v[154:155], v[244:245], 0, s[36:37]
	s_mov_b32 m0, s63
	s_nop 0
	global_load_lds_dwordx4 v[154:155], off
	s_barrier
	s_waitcnt lgkmcnt(0)
	s_setprio 1
	s_waitcnt lgkmcnt(0)
	v_mfma_f32_16x16x32_bf16 v[66:69], v[150:153], v[170:173], v[66:69]
	v_mfma_f32_16x16x32_bf16 v[62:65], v[162:165], v[170:173], v[62:65]
	v_mfma_f32_16x16x32_bf16 v[50:53], v[150:153], v[178:181], v[50:53]
	v_mfma_f32_16x16x32_bf16 v[46:49], v[162:165], v[178:181], v[46:49]
	v_mfma_f32_16x16x32_bf16 v[34:37], v[150:153], v[200:203], v[34:37]
	v_mfma_f32_16x16x32_bf16 v[30:33], v[162:165], v[200:203], v[30:33]
	v_mfma_f32_16x16x32_bf16 v[18:21], v[150:153], v[208:211], v[18:21]
	v_mfma_f32_16x16x32_bf16 v[8:11], v[162:165], v[208:211], v[8:11]
	v_mfma_f32_16x16x32_bf16 v[66:69], v[158:161], v[174:177], v[66:69]
	v_mfma_f32_16x16x32_bf16 v[62:65], v[166:169], v[174:177], v[62:65]
	v_mfma_f32_16x16x32_bf16 v[50:53], v[158:161], v[196:199], v[50:53]
	v_mfma_f32_16x16x32_bf16 v[46:49], v[166:169], v[196:199], v[46:49]
	v_mfma_f32_16x16x32_bf16 v[34:37], v[158:161], v[204:207], v[34:37]
	v_mfma_f32_16x16x32_bf16 v[30:33], v[166:169], v[204:207], v[30:33]
	v_mfma_f32_16x16x32_bf16 v[18:21], v[158:161], v[212:215], v[18:21]
	v_mfma_f32_16x16x32_bf16 v[8:11], v[166:169], v[212:215], v[8:11]
	s_setprio 0
	s_barrier
	s_add_u32 s48, s48, 0x80080
	s_addc_u32 s49, s49, 0
	s_add_i32 s8, s9, s56
	v_lshl_add_u64 v[150:151], s[48:49], 0, v[136:137]
	s_mov_b32 m0, s8
	s_nop 0
	global_load_lds_dwordx4 v[150:151], off
	v_lshl_add_u64 v[150:151], s[48:49], 0, v[140:141]
	s_add_i32 m0, s8, 0x2000
	s_nop 0
	global_load_lds_dwordx4 v[150:151], off
	s_waitcnt vmcnt(6)
	s_barrier
	s_setprio 1
	v_add_u32_e32 v154, 0x10000, v13
	v_mfma_f32_16x16x32_bf16 v[58:61], v[216:219], v[170:173], v[58:61]
	v_mfma_f32_16x16x32_bf16 v[54:57], v[236:239], v[170:173], v[54:57]
	v_mfma_f32_16x16x32_bf16 v[42:45], v[216:219], v[178:181], v[42:45]
	v_mfma_f32_16x16x32_bf16 v[38:41], v[236:239], v[178:181], v[38:41]
	ds_read_b128 v[150:153], v154
	v_mfma_f32_16x16x32_bf16 v[26:29], v[216:219], v[200:203], v[26:29]
	v_mfma_f32_16x16x32_bf16 v[22:25], v[236:239], v[200:203], v[22:25]
	ds_read_b128 v[158:161], v154 offset:1024
	v_mfma_f32_16x16x32_bf16 v[4:7], v[216:219], v[208:211], v[4:7]
	v_mfma_f32_16x16x32_bf16 v[0:3], v[236:239], v[208:211], v[0:3]
	ds_read_b128 v[162:165], v154 offset:2048
	v_mfma_f32_16x16x32_bf16 v[58:61], v[220:223], v[174:177], v[58:61]
	v_mfma_f32_16x16x32_bf16 v[54:57], v[240:243], v[174:177], v[54:57]
	ds_read_b128 v[166:169], v154 offset:3072
	v_mfma_f32_16x16x32_bf16 v[42:45], v[220:223], v[196:199], v[42:45]
	v_mfma_f32_16x16x32_bf16 v[38:41], v[240:243], v[196:199], v[38:41]
	v_mfma_f32_16x16x32_bf16 v[26:29], v[220:223], v[204:207], v[26:29]
	v_mfma_f32_16x16x32_bf16 v[22:25], v[240:243], v[204:207], v[22:25]
	v_mfma_f32_16x16x32_bf16 v[4:7], v[220:223], v[212:215], v[4:7]
	v_mfma_f32_16x16x32_bf16 v[0:3], v[240:243], v[212:215], v[0:3]
	s_setprio 0
	s_add_i32 s29, s29, 2
	s_add_u32 s3, s3, 0x100
	s_addc_u32 s24, s24, 0
	s_add_u32 s46, s46, 0x100
	s_addc_u32 s47, s47, 0
	s_cmp_gt_u32 s29, 29
	s_barrier
	s_cbranch_scc0 .Lk1_body
	s_waitcnt lgkmcnt(0)
	s_lshl_b32 s3, s40, 8
	s_sub_i32 s8, s65, 18
	s_add_i32 s3, s3, s61
	s_lshl_b32 s24, s65, 8
	s_cmp_gt_u32 s8, 23
	v_or_b32_e32 v158, s3, v12
	s_mov_b64 s[40:41], -1
	s_cbranch_scc0 .LBB0_1295
	s_cmp_gt_i32 s65, 1
	s_cselect_b64 s[46:47], -1, 0
	v_mad_i64_i32 v[150:151], s[40:41], v158, s4, 0
	v_or_b32_e32 v182, s24, v156
	s_mov_b64 s[40:41], -1
	s_and_b64 vcc, exec, s[46:47]
	v_lshl_add_u64 v[150:151], s[0:1], 0, v[150:151]
	s_cbranch_vccz .LBB0_1232
	v_lshl_add_u64 v[152:153], v[182:183], 1, v[150:151]
	s_mov_b64 s[40:41], 0
